# v87 + mLSTM scan: workgroup barrier B6 removed (the state write-back it guarded is already ordered by B4/B5 before and B1 after)
# baseline (speedup 1.0000x reference)
.LBB0_227:
	v_add_u32_e32 v89, s86, v214
	v_add_u32_e32 v94, s86, v212
	ds_read_b128 v[90:93], v89 offset:34816
	v_add_u32_e32 v95, 0x19800, v94
	v_add_u32_e32 v98, 0x1a900, v94
	ds_read_b128 v[94:97], v95
	ds_read_b128 v[98:101], v98
	ds_read_b128 v[246:249], v89 offset:39168
	v_add_u32_e32 v102, 0x11000, v89
	v_add_u32_e32 v245, 0x12100, v89
	ds_read_b128 v[250:253], v102
	ds_read_b128 v[102:105], v245
	s_add_i32 s86, s86, 64
	s_cmpk_eq_i32 s86, 0x100
	s_waitcnt lgkmcnt(4)
	v_mfma_f32_16x16x32_bf16 v[84:87], v[90:93], v[94:97], v[84:87]
	s_waitcnt lgkmcnt(3)
	v_mfma_f32_16x16x32_bf16 v[80:83], v[90:93], v[98:101], v[80:83]
	s_waitcnt lgkmcnt(2)
	v_mfma_f32_16x16x32_bf16 v[76:79], v[246:249], v[94:97], v[76:79]
	v_mfma_f32_16x16x32_bf16 v[72:75], v[246:249], v[98:101], v[72:75]
	s_waitcnt lgkmcnt(1)
	v_mfma_f32_16x16x32_bf16 v[56:59], v[250:253], v[94:97], v[56:59]
	v_mfma_f32_16x16x32_bf16 v[60:63], v[250:253], v[98:101], v[60:63]
	s_waitcnt lgkmcnt(0)
	v_mfma_f32_16x16x32_bf16 v[64:67], v[102:105], v[94:97], v[64:67]
	v_mfma_f32_16x16x32_bf16 v[68:71], v[102:105], v[98:101], v[68:71]
	s_cbranch_scc0 .LBB0_227
	ds_read_b128 v[90:93], v216
	ds_read_b128 v[94:97], v216 offset:16
	ds_read_b128 v[98:101], v216 offset:32
	ds_read_b128 v[102:105], v216 offset:48
	s_lshl_b32 s84, s84, 7
	s_sub_i32 s90, s94, s84
	s_and_b64 s[86:87], s[2:3], exec
	s_waitcnt lgkmcnt(3)
	v_lshlrev_b32_e32 v89, 16, v90
	v_and_b32_e32 v90, 0xffff0000, v90
	v_add_f32_e32 v89, v89, v90
	v_lshlrev_b32_e32 v90, 16, v91
	v_and_b32_e32 v91, 0xffff0000, v91
	v_add_f32_e32 v90, v90, v91
	v_add_f32_e32 v89, v89, v90
	v_lshlrev_b32_e32 v90, 16, v92
	v_and_b32_e32 v91, 0xffff0000, v92
	v_add_f32_e32 v90, v90, v91
	v_add_f32_e32 v89, v90, v89
	v_lshlrev_b32_e32 v90, 16, v93
	v_and_b32_e32 v91, 0xffff0000, v93
	v_add_f32_e32 v90, v90, v91
	v_add_f32_e32 v89, v90, v89
	s_waitcnt lgkmcnt(2)
	v_lshlrev_b32_e32 v90, 16, v94
	v_and_b32_e32 v91, 0xffff0000, v94
	v_add_f32_e32 v90, v90, v91
	v_lshlrev_b32_e32 v91, 16, v95
	v_and_b32_e32 v92, 0xffff0000, v95
	v_add_f32_e32 v91, v91, v92
	v_add_f32_e32 v90, v90, v91
	v_lshlrev_b32_e32 v91, 16, v96
	v_and_b32_e32 v92, 0xffff0000, v96
	v_add_f32_e32 v91, v91, v92
	v_add_f32_e32 v90, v91, v90
	v_lshlrev_b32_e32 v91, 16, v97
	v_and_b32_e32 v92, 0xffff0000, v97
	v_add_f32_e32 v91, v91, v92
	v_add_f32_e32 v89, 0, v89
	v_add_f32_e32 v90, v91, v90
	v_add_f32_e32 v89, v89, v90
	s_waitcnt lgkmcnt(1)
	v_lshlrev_b32_e32 v90, 16, v98
	v_and_b32_e32 v91, 0xffff0000, v98
	v_add_f32_e32 v90, v90, v91
	v_lshlrev_b32_e32 v91, 16, v99
	v_and_b32_e32 v92, 0xffff0000, v99
	v_add_f32_e32 v91, v91, v92
	v_add_f32_e32 v90, v90, v91
	v_lshlrev_b32_e32 v91, 16, v100
	v_and_b32_e32 v92, 0xffff0000, v100
	v_add_f32_e32 v91, v91, v92
	v_add_f32_e32 v90, v91, v90
	v_lshlrev_b32_e32 v91, 16, v101
	v_and_b32_e32 v92, 0xffff0000, v101
	v_add_f32_e32 v91, v91, v92
	v_add_f32_e32 v90, v91, v90
	v_add_f32_e32 v89, v89, v90
	s_waitcnt lgkmcnt(0)
	v_lshlrev_b32_e32 v90, 16, v102
	v_and_b32_e32 v91, 0xffff0000, v102
	v_add_f32_e32 v90, v90, v91
	v_lshlrev_b32_e32 v91, 16, v103
	v_and_b32_e32 v92, 0xffff0000, v103
	v_add_f32_e32 v91, v91, v92
	v_add_f32_e32 v90, v90, v91
	v_lshlrev_b32_e32 v91, 16, v104
	v_and_b32_e32 v92, 0xffff0000, v104
	v_add_f32_e32 v91, v91, v92
	v_add_f32_e32 v90, v91, v90
	v_lshlrev_b32_e32 v91, 16, v105
	v_and_b32_e32 v92, 0xffff0000, v105
	v_add_f32_e32 v91, v91, v92
	s_cselect_b32 s84, s84, s90
	ds_read_b128 v[92:95], v182
	s_add_i32 s84, s84, s89
	v_or_b32_e32 v96, s84, v200
	v_ashrrev_i32_e32 v97, 31, v96
	v_lshlrev_b64 v[96:97], 11, v[96:97]
	v_lshl_add_u64 v[100:101], v[146:147], 0, v[96:97]
	ds_read_b128 v[96:99], v182 offset:64
	s_waitcnt lgkmcnt(1)
	v_mul_f32_e32 v84, v84, v92
	v_mul_f32_e32 v80, v80, v92
	v_cvt_pk_bf16_f32 v84, v84, v84
	global_store_short v[100:101], v84, off
	v_cvt_pk_bf16_f32 v80, v80, v80
	global_store_short v[100:101], v80, off offset:32
	v_or_b32_e32 v100, s84, v201
	v_ashrrev_i32_e32 v101, 31, v100
	v_lshlrev_b64 v[100:101], 11, v[100:101]
	v_mul_f32_e32 v80, v85, v93
	v_lshl_add_u64 v[100:101], v[146:147], 0, v[100:101]
	v_cvt_pk_bf16_f32 v80, v80, v80
	global_store_short v[100:101], v80, off
	v_mul_f32_e32 v80, v81, v93
	v_cvt_pk_bf16_f32 v80, v80, v80
	global_store_short v[100:101], v80, off offset:32
	v_or_b32_e32 v80, s84, v203
	v_ashrrev_i32_e32 v81, 31, v80
	v_lshlrev_b64 v[80:81], 11, v[80:81]
	v_lshl_add_u64 v[80:81], v[146:147], 0, v[80:81]
	v_mul_f32_e32 v84, v86, v94
	v_mul_f32_e32 v82, v82, v94
	v_cvt_pk_bf16_f32 v84, v84, v84
	global_store_short v[80:81], v84, off
	v_cvt_pk_bf16_f32 v82, v82, v82
	global_store_short v[80:81], v82, off offset:32
	v_or_b32_e32 v80, s84, v204
	v_ashrrev_i32_e32 v81, 31, v80
	v_lshlrev_b64 v[80:81], 11, v[80:81]
	v_mul_f32_e32 v82, v87, v95
	v_lshl_add_u64 v[80:81], v[146:147], 0, v[80:81]
	v_cvt_pk_bf16_f32 v82, v82, v82
	global_store_short v[80:81], v82, off
	v_mul_f32_e32 v82, v83, v95
	v_cvt_pk_bf16_f32 v82, v82, v82
	global_store_short v[80:81], v82, off offset:32
	v_or_b32_e32 v80, s84, v205
	v_ashrrev_i32_e32 v81, 31, v80
	v_lshlrev_b64 v[80:81], 11, v[80:81]
	v_lshl_add_u64 v[80:81], v[146:147], 0, v[80:81]
	s_waitcnt lgkmcnt(0)
	v_mul_f32_e32 v76, v76, v96
	v_mul_f32_e32 v72, v72, v96
	v_cvt_pk_bf16_f32 v76, v76, v76
	global_store_short v[80:81], v76, off
	v_cvt_pk_bf16_f32 v72, v72, v72
	global_store_short v[80:81], v72, off offset:32
	v_or_b32_e32 v80, s84, v206
	v_ashrrev_i32_e32 v81, 31, v80
	v_lshlrev_b64 v[80:81], 11, v[80:81]
	v_mul_f32_e32 v72, v77, v97
	v_add_f32_e32 v90, v91, v90
	v_lshl_add_u64 v[80:81], v[146:147], 0, v[80:81]
	v_cvt_pk_bf16_f32 v72, v72, v72
	v_add_f32_e32 v89, v89, v90
	global_store_short v[80:81], v72, off
	v_mul_f32_e32 v72, v73, v97
	s_nop 1
	v_add_f32_dpp v89, v89, v89 quad_perm:[1,0,3,2] row_mask:0xf bank_mask:0xf
	v_cvt_pk_bf16_f32 v72, v72, v72
	global_store_short v[80:81], v72, off offset:32
	v_or_b32_e32 v72, s84, v207
	v_ashrrev_i32_e32 v73, 31, v72
	v_lshlrev_b64 v[72:73], 11, v[72:73]
	v_lshl_add_u64 v[72:73], v[146:147], 0, v[72:73]
	v_mul_f32_e32 v76, v78, v98
	v_mul_f32_e32 v74, v74, v98
	s_waitcnt lgkmcnt(0)
	s_nop 0
	v_cvt_pk_bf16_f32 v76, v76, v76
	global_store_short v[72:73], v76, off
	v_cvt_pk_bf16_f32 v74, v74, v74
	global_store_short v[72:73], v74, off offset:32
	v_or_b32_e32 v72, s84, v208
	v_mov_b32_dpp v90, v89 quad_perm:[2,3,0,1] row_mask:0xf bank_mask:0xf
	v_ashrrev_i32_e32 v73, 31, v72
	v_lshlrev_b64 v[72:73], 11, v[72:73]
	v_mul_f32_e32 v74, v79, v99
	v_lshl_add_u64 v[72:73], v[146:147], 0, v[72:73]
	v_cvt_pk_bf16_f32 v74, v74, v74
	global_store_short v[72:73], v74, off
	v_mul_f32_e32 v74, v75, v99
	v_cvt_pk_bf16_f32 v76, v64, v65
	v_cvt_pk_bf16_f32 v74, v74, v74
	global_store_short v[72:73], v74, off offset:32
	s_waitcnt lgkmcnt(0)
	ds_read_b32 v245, v134
	v_cvt_pk_bf16_f32 v72, v56, v57
	v_cvt_pk_bf16_f32 v73, v58, v59
	v_cvt_pk_bf16_f32 v77, v66, v67
	ds_write2_b64 v217, v[72:73], v[76:77] offset1:4
	v_add_u32_e32 v76, 0x1000, v217
	v_cvt_pk_bf16_f32 v74, v60, v61
	v_cvt_pk_bf16_f32 v75, v62, v63
	v_cvt_pk_bf16_f32 v72, v68, v69
	v_cvt_pk_bf16_f32 v73, v70, v71
	ds_write2_b64 v76, v[74:75], v[72:73] offset0:32 offset1:36
	s_and_saveexec_b64 s[86:87], s[6:7]
	s_cbranch_execz .LBB0_201
	s_waitcnt lgkmcnt(2)
	v_add_f32_e32 v72, v89, v90
	v_mov_b32_e32 v73, v245
	v_fmac_f32_e32 v72, v88, v73
	ds_write_b32 v134, v72
	s_branch .LBB0_201
